# GDN head-output epilogue (P3b): 16 short stores per item paired into 8 dword stores via a DPP lane-pair exchange; on top of acquire-at-arrival
# baseline (speedup 1.0000x reference)
.LBB0_1029:
	s_cmpk_gt_i32 s2, 0xfff
	s_cbranch_scc1 .LBB0_1032
	s_add_u32 s15, s20, 0x17348000
	s_addc_u32 s16, s21, 0
	s_add_u32 s100, s20, 0x10000
	s_addc_u32 s101, s21, 0
	s_waitcnt vmcnt(30)
	v_mbcnt_hi_u32_b32 v20, -1, v183
	s_add_u32 s17, s20, 0x15248000
	v_and_b32_e32 v0, 64, v20
	s_mov_b32 s0, 0x358637bd
	s_addc_u32 s29, s21, 0
	s_mov_b32 s9, 0
	v_mov_b32_e32 v9, 0
	s_mov_b64 s[10:11], 0x1000
	s_mov_b64 s[12:13], 0x1800
	s_movk_i32 s34, 0x1000
	v_xor_b32_e32 v21, 1, v20
	v_add_u32_e32 v22, 64, v0
	v_xor_b32_e32 v23, 2, v20
	s_waitcnt vmcnt(29)
	v_xor_b32_e32 v24, 4, v20
	v_xor_b32_e32 v25, 8, v20
	s_mov_b32 s14, 0x3c800000
	v_mov_b64_e32 v[10:11], s[0:1]
	s_mov_b32 s35, 0x800000
	s_movk_i32 s36, 0x2000
	s_movk_i32 s37, 0x4000
	s_movk_i32 s38, 0x6000
	s_mov_b32 s39, s2
	s_mov_b32 s72, 0x55555555
	s_mov_b32 s73, 0x55555555
.LBB0_1031:
	v_cmp_lt_i32_e32 vcc, v21, v22
	v_mov_b32_e32 v0, v181
	s_ashr_i32 s0, s39, 3
	v_cndmask_b32_e32 v2, v20, v21, vcc
	v_cmp_lt_i32_e32 vcc, v23, v22
	s_waitcnt vmcnt(28)
	v_lshlrev_b32_e32 v33, 2, v2
	v_ashrrev_i32_e32 v2, 6, v0
	v_cndmask_b32_e32 v3, v20, v23, vcc
	v_cmp_lt_i32_e32 vcc, v24, v22
	v_lshlrev_b32_e32 v32, 2, v3
	v_and_b32_e32 v3, 63, v0
	v_cndmask_b32_e32 v4, v20, v24, vcc
	v_cmp_lt_i32_e32 vcc, v25, v22
	v_lshlrev_b32_e32 v31, 2, v4
	v_and_b32_e32 v4, 15, v0
	v_cndmask_b32_e32 v5, v20, v25, vcc
	v_lshlrev_b32_e32 v30, 2, v5
	v_lshrrev_b32_e32 v0, 2, v0
	v_lshlrev_b32_e32 v5, 4, v2
	s_lshl_b32 s1, s39, 7
	v_and_b32_e32 v6, 12, v0
	v_lshlrev_b32_e32 v7, 2, v3
	v_lshlrev_b32_e32 v12, 5, v3
	v_lshl_add_u32 v3, s0, 6, v5
	s_and_b32 s4, s39, 0xfffffc00
	s_and_b32 s8, s1, 0x380
	v_lshlrev_b32_e32 v8, 1, v4
	v_lshlrev_b32_e32 v0, 2, v4
	v_or_b32_e32 v5, v5, v4
	v_or_b32_e32 v4, v3, v6
	s_and_b32 s1, s0, 0x7f
	s_or_b32 s4, s8, s4
	global_load_dword v29, v0, s[40:41]
	global_load_dword v28, v0, s[40:41] offset:64
	global_load_dword v27, v0, s[40:41] offset:128
	global_load_dword v26, v0, s[40:41] offset:192
	v_lshlrev_b32_e32 v0, 1, v6
	v_lshlrev_b32_e32 v6, 6, v5
	v_ashrrev_i32_e32 v5, 31, v4
	s_or_b32 s4, s4, s1
	s_waitcnt vmcnt(28)
	v_lshlrev_b64 v[66:67], 13, v[4:5]
	s_ashr_i32 s5, s4, 31
	v_or_b32_e32 v14, 1, v4
	v_or_b32_e32 v16, 2, v4
	v_or_b32_e32 v18, 3, v4
	v_lshl_add_u64 v[4:5], s[20:21], 0, v[66:67]
	s_lshl_b64 s[0:1], s[4:5], 13
	v_lshl_add_u64 v[4:5], v[4:5], 0, s[8:9]
	s_add_u32 s4, s50, s0
	v_lshl_add_u64 v[50:51], v[4:5], 0, v[8:9]
	s_addc_u32 s5, s51, s1
	v_add_co_u32_e32 v52, vcc, s36, v50
	s_add_u32 s6, s17, s0
	s_nop 0
	v_addc_co_u32_e32 v53, vcc, 0, v51, vcc
	v_lshl_or_b32 v2, v2, 10, v7
	v_ashrrev_i32_e32 v7, 31, v6
	s_addc_u32 s7, s29, s1
	v_add_co_u32_e32 v54, vcc, s37, v50
	v_mov_b32_e32 v1, v9
	v_ashrrev_i32_e32 v3, 31, v2
	v_lshl_add_u64 v[6:7], v[6:7], 1, s[4:5]
	s_add_u32 s0, s15, s0
	v_addc_co_u32_e32 v55, vcc, 0, v51, vcc
	v_mov_b32_e32 v13, v9
	v_lshl_add_u64 v[34:35], v[6:7], 0, v[0:1]
	v_lshl_add_u64 v[36:37], v[2:3], 1, s[6:7]
	s_addc_u32 s1, s16, s1
	v_add_co_u32_e32 v56, vcc, s38, v50
	global_load_dwordx2 v[4:5], v[34:35], off
	global_load_dwordx2 v[6:7], v[34:35], off offset:32
	global_load_dwordx2 v[0:1], v[34:35], off offset:64
	global_load_dwordx2 v[2:3], v[34:35], off offset:96
	global_load_dwordx2 v[68:69], v[36:37], off
	global_load_dwordx2 v[72:73], v[36:37], off offset:512
	global_load_dwordx2 v[76:77], v[36:37], off offset:1024
	global_load_dwordx2 v[80:81], v[36:37], off offset:1536
	v_addc_co_u32_e32 v57, vcc, 0, v51, vcc
	global_load_ushort v82, v[50:51], off offset:3072
	global_load_ushort v83, v[50:51], off offset:3104
	global_load_ushort v84, v[50:51], off offset:3136
	global_load_ushort v85, v[50:51], off offset:3168
	global_load_dwordx4 v[34:37], v12, s[0:1]
	global_load_dwordx4 v[38:41], v12, s[0:1] offset:2048
	global_load_dwordx4 v[42:45], v12, s[0:1] offset:16
	global_load_dwordx4 v[46:49], v12, s[0:1] offset:2064
	global_load_ushort v86, v[52:53], off offset:3072
	global_load_ushort v87, v[54:55], off offset:3072
	global_load_ushort v88, v[56:57], off offset:3072
	global_load_ushort v89, v[52:53], off offset:3104
	global_load_ushort v90, v[54:55], off offset:3104
	global_load_ushort v91, v[56:57], off offset:3104
	global_load_ushort v92, v[52:53], off offset:3136
	global_load_ushort v93, v[54:55], off offset:3136
	global_load_ushort v94, v[56:57], off offset:3136
	global_load_ushort v95, v[54:55], off offset:3168
	global_load_ushort v96, v[52:53], off offset:3168
	global_load_ushort v97, v[56:57], off offset:3168
	v_lshl_add_u64 v[12:13], s[0:1], 0, v[12:13]
	v_lshl_add_u64 v[70:71], v[12:13], 0, s[10:11]
	s_waitcnt vmcnt(55)
	v_lshl_add_u64 v[74:75], v[12:13], 0, s[12:13]
	v_add_co_u32_e32 v12, vcc, s34, v12
	s_add_u32 s0, s20, s8
	s_nop 0
	v_addc_co_u32_e32 v13, vcc, 0, v13, vcc
	global_load_dwordx4 v[50:53], v[12:13], off
	global_load_dwordx4 v[54:57], v[12:13], off offset:2048
	global_load_dwordx4 v[58:61], v[70:71], off offset:16
	global_load_dwordx4 v[62:65], v[74:75], off offset:16
	s_addc_u32 s1, s21, 0
	v_and_b32_e32 v12, 0xffe00000, v66
	v_lshrrev_b32_e32 v13, 5, v66
	v_and_b32_e32 v13, 0xe000, v13
	v_lshrrev_b32_e32 v14, 7, v66
	v_and_b32_e32 v14, 0x7c0, v14
	v_lshrrev_b32_e32 v15, 10, v66
	v_and_b32_e32 v15, 32, v15
	v_and_b32_e32 v16, 30, v8
	v_or3_b32 v12, v12, v13, v14
	v_or3_b32 v12, v12, v15, v16
	s_lshl_b32 s8, s8, 10
	v_add_u32_e32 v12, s8, v12
	v_xor_b32_e32 v16, 16, v12
	v_add_u32_e32 v14, 64, v12
	v_add_u32_e32 v18, 0xc0, v16
	v_add_u32_e32 v16, 0x80, v16
	v_xor_b32_e32 v13, 32, v12
	v_xor_b32_e32 v15, 32, v14
	v_xor_b32_e32 v17, 32, v16
	v_xor_b32_e32 v19, 32, v18
	v_add_u32_e32 v14, -2, v14
	v_add_u32_e32 v15, -2, v15
	v_add_u32_e32 v18, -2, v18
	v_add_u32_e32 v19, -2, v19
	v_cndmask_b32_e64 v12, v14, v12, s[72:73]
	v_cndmask_b32_e64 v13, v15, v13, s[72:73]
	v_cndmask_b32_e64 v16, v18, v16, s[72:73]
	v_cndmask_b32_e64 v17, v19, v17, s[72:73]
	s_add_i32 s39, s39, s22
	s_cmpk_lt_i32 s39, 0x1000
	s_waitcnt vmcnt(23)
	v_lshlrev_b32_e32 v8, 16, v82
	s_waitcnt vmcnt(22)
	v_lshlrev_b32_e32 v98, 16, v83
	s_waitcnt vmcnt(21)
	v_lshlrev_b32_e32 v99, 16, v84
	s_waitcnt vmcnt(20)
	v_lshlrev_b32_e32 v100, 16, v85
	s_waitcnt vmcnt(19)
	v_mov_b32_e32 v82, v34
	v_mov_b32_e32 v83, v35
	s_waitcnt vmcnt(18)
	v_mov_b32_e32 v84, v38
	v_mov_b32_e32 v85, v39
	s_waitcnt vmcnt(17)
	v_mov_b32_e32 v34, v42
	v_mov_b32_e32 v35, v43
	v_mul_f32_e32 v42, 0xbfb8aa3b, v8
	v_mul_f32_e32 v43, 0xbfb8aa3b, v98
	v_mov_b32_e32 v38, v36
	v_mov_b32_e32 v39, v37
	v_lshlrev_b32_e32 v66, 16, v68
	v_and_b32_e32 v67, 0xffff0000, v68
	v_lshlrev_b32_e32 v68, 16, v69
	v_and_b32_e32 v69, 0xffff0000, v69
	v_lshlrev_b32_e32 v70, 16, v72
	v_and_b32_e32 v71, 0xffff0000, v72
	v_lshlrev_b32_e32 v72, 16, v73
	v_and_b32_e32 v73, 0xffff0000, v73
	s_waitcnt vmcnt(16)
	v_mov_b32_e32 v36, v46
	v_mov_b32_e32 v37, v47
	v_mov_b32_e32 v46, v44
	v_mov_b32_e32 v47, v45
	v_exp_f32_e32 v103, v42
	v_exp_f32_e32 v107, v43
	v_mfma_f32_16x16x32_bf16 v[42:45], v[4:7], v[82:85], v[66:69]
	v_lshlrev_b32_e32 v74, 16, v76
	v_and_b32_e32 v75, 0xffff0000, v76
	v_lshlrev_b32_e32 v76, 16, v77
	v_and_b32_e32 v77, 0xffff0000, v77
	v_lshlrev_b32_e32 v78, 16, v80
	v_and_b32_e32 v79, 0xffff0000, v80
	v_lshlrev_b32_e32 v80, 16, v81
	v_and_b32_e32 v81, 0xffff0000, v81
	s_waitcnt vmcnt(15)
	v_lshlrev_b32_e32 v86, 16, v86
	s_waitcnt vmcnt(14)
	v_lshlrev_b32_e32 v87, 16, v87
	v_mul_f32_e32 v101, 0xbfb8aa3b, v99
	v_mfma_f32_16x16x32_bf16 v[38:41], v[4:7], v[38:41], v[70:73]
	s_waitcnt vmcnt(8)
	v_lshlrev_b32_e32 v93, 16, v93
	s_waitcnt vmcnt(7)
	v_lshlrev_b32_e32 v94, 16, v94
	v_mul_f32_e32 v104, 0xbfb8aa3b, v86
	v_mul_f32_e32 v105, 0xbfb8aa3b, v87
	v_exp_f32_e32 v67, v101
	v_mfma_f32_16x16x32_bf16 v[34:37], v[4:7], v[34:37], v[74:77]
	v_lshlrev_b32_e32 v88, 16, v88
	v_lshlrev_b32_e32 v89, 16, v89
	v_lshlrev_b32_e32 v90, 16, v90
	v_mfma_f32_16x16x32_bf16 v[4:7], v[4:7], v[46:49], v[78:81]
	v_lshlrev_b32_e32 v92, 16, v92
	s_waitcnt vmcnt(5)
	v_lshlrev_b32_e32 v96, 16, v96
	v_lshlrev_b32_e32 v95, 16, v95
	v_mul_f32_e32 v69, 0xbfb8aa3b, v93
	v_mul_f32_e32 v70, 0xbfb8aa3b, v94
	s_waitcnt vmcnt(3)
	v_mov_b32_e32 v46, v50
	v_mov_b32_e32 v47, v51
	s_waitcnt vmcnt(2)
	v_mov_b32_e32 v48, v54
	v_mov_b32_e32 v49, v55
	s_waitcnt vmcnt(1)
	v_mov_b32_e32 v50, v58
	v_mov_b32_e32 v51, v59
	v_exp_f32_e32 v58, v104
	v_exp_f32_e32 v59, v105
	v_lshlrev_b32_e32 v91, 16, v91
	v_mul_f32_e32 v102, 0xbfb8aa3b, v100
	v_lshlrev_b32_e32 v97, 16, v97
	v_mul_f32_e32 v106, 0xbfb8aa3b, v88
	v_mul_f32_e32 v108, 0xbfb8aa3b, v89
	v_mul_f32_e32 v109, 0xbfb8aa3b, v90
	v_mul_f32_e32 v68, 0xbfb8aa3b, v92
	v_mul_f32_e32 v72, 0xbfb8aa3b, v96
	v_mul_f32_e32 v73, 0xbfb8aa3b, v95
	v_mov_b32_e32 v54, v52
	v_mov_b32_e32 v55, v53
	v_mfma_f32_16x16x32_bf16 v[42:45], v[0:3], v[46:49], v[42:45]
	v_exp_f32_e32 v46, v69
	v_exp_f32_e32 v47, v70
	v_mul_f32_e32 v66, 0xbfb8aa3b, v91
	v_exp_f32_e32 v71, v102
	v_mul_f32_e32 v74, 0xbfb8aa3b, v97
	s_waitcnt vmcnt(0)
	v_mov_b32_e32 v52, v62
	v_mov_b32_e32 v53, v63
	v_mov_b32_e32 v62, v60
	v_mov_b32_e32 v63, v61
	v_exp_f32_e32 v60, v106
	v_exp_f32_e32 v61, v108
	v_exp_f32_e32 v75, v109
	v_exp_f32_e32 v68, v68
	v_exp_f32_e32 v48, v72
	v_mfma_f32_16x16x32_bf16 v[38:41], v[0:3], v[54:57], v[38:41]
	v_exp_f32_e32 v49, v73
	v_exp_f32_e32 v66, v66
	v_exp_f32_e32 v54, v74
	v_add_f32_e32 v55, 1.0, v103
	v_mfma_f32_16x16x32_bf16 v[34:37], v[0:3], v[50:53], v[34:37]
	v_add_f32_e32 v50, 1.0, v107
	v_add_f32_e32 v51, 1.0, v67
	v_add_f32_e32 v46, 1.0, v46
	v_mfma_f32_16x16x32_bf16 v[0:3], v[0:3], v[62:65], v[4:7]
	v_rcp_f32_e32 v62, v55
	v_add_f32_e32 v47, 1.0, v47
	v_add_f32_e32 v52, 1.0, v71
	v_add_f32_e32 v4, 1.0, v58
	v_add_f32_e32 v5, 1.0, v59
	v_rcp_f32_e32 v58, v50
	v_rcp_f32_e32 v59, v51
	v_add_f32_e32 v6, 1.0, v60
	v_add_f32_e32 v7, 1.0, v61
	v_add_f32_e32 v50, 1.0, v75
	v_add_f32_e32 v51, 1.0, v68
	v_add_f32_e32 v48, 1.0, v48
	v_add_f32_e32 v49, 1.0, v49
	v_rcp_f32_e32 v61, v4
	v_rcp_f32_e32 v63, v5
	v_rcp_f32_e32 v69, v46
	v_rcp_f32_e32 v70, v47
	v_mov_b32_e32 v4, v42
	v_mov_b32_e32 v5, v38
	v_mov_b32_e32 v46, v43
	v_mov_b32_e32 v47, v39
	v_add_f32_e32 v53, 1.0, v66
	v_rcp_f32_e32 v60, v52
	v_add_f32_e32 v52, 1.0, v54
	v_rcp_f32_e32 v64, v6
	v_rcp_f32_e32 v65, v7
	v_rcp_f32_e32 v66, v50
	v_rcp_f32_e32 v68, v51
	v_rcp_f32_e32 v71, v48
	v_rcp_f32_e32 v72, v49
	v_mov_b32_e32 v6, v34
	v_mov_b32_e32 v7, v0
	v_mov_b32_e32 v48, v35
	v_mov_b32_e32 v49, v1
	v_mov_b32_e32 v50, v44
	v_mov_b32_e32 v51, v40
	v_mov_b32_e32 v54, v45
	v_mov_b32_e32 v55, v41
	v_pk_mul_f32 v[4:5], v[4:5], v[4:5]
	v_pk_mul_f32 v[46:47], v[46:47], v[46:47]
	v_rcp_f32_e32 v67, v53
	v_rcp_f32_e32 v73, v52
	v_mov_b32_e32 v52, v36
	v_mov_b32_e32 v53, v2
	v_mov_b32_e32 v56, v37
	v_mov_b32_e32 v57, v3
	v_mul_f32_e32 v8, v62, v8
	v_mul_f32_e32 v62, v58, v98
	v_mul_f32_e32 v74, v59, v99
	v_pk_mul_f32 v[6:7], v[6:7], v[6:7]
	v_pk_mul_f32 v[48:49], v[48:49], v[48:49]
	v_pk_mul_f32 v[50:51], v[50:51], v[50:51]
	v_pk_mul_f32 v[54:55], v[54:55], v[54:55]
	v_mov_b32_e32 v58, v46
	v_mov_b32_e32 v59, v4
	v_mov_b32_e32 v4, v47
	v_pk_mul_f32 v[52:53], v[52:53], v[52:53]
	v_pk_mul_f32 v[56:57], v[56:57], v[56:57]
	v_mov_b32_e32 v46, v48
	v_mov_b32_e32 v47, v6
	v_mov_b32_e32 v6, v49
	v_mov_b32_e32 v48, v54
	v_mov_b32_e32 v49, v50
	v_mov_b32_e32 v50, v55
	v_pk_add_f32 v[4:5], v[58:59], v[4:5]
	v_mov_b32_e32 v54, v56
	v_mov_b32_e32 v55, v52
	v_pk_add_f32 v[48:49], v[48:49], v[50:51]
	v_pk_add_f32 v[4:5], v[4:5], v[46:47]
	v_mov_b32_e32 v52, v57
	v_pk_add_f32 v[46:47], v[48:49], v[54:55]
	v_pk_add_f32 v[4:5], v[4:5], v[6:7]
	v_pk_add_f32 v[6:7], v[46:47], v[52:53]
	ds_bpermute_b32 v47, v33, v5
	ds_bpermute_b32 v46, v33, v4
	ds_bpermute_b32 v49, v33, v7
	ds_bpermute_b32 v48, v33, v6
	v_mul_f32_e32 v60, v60, v100
	v_mul_f32_e32 v61, v61, v86
	s_waitcnt lgkmcnt(2)
	v_pk_add_f32 v[4:5], v[4:5], v[46:47]
	ds_bpermute_b32 v47, v32, v5
	s_waitcnt lgkmcnt(1)
	v_pk_add_f32 v[6:7], v[6:7], v[48:49]
	ds_bpermute_b32 v46, v32, v4
	ds_bpermute_b32 v33, v32, v7
	ds_bpermute_b32 v32, v32, v6
	v_mul_f32_e32 v63, v63, v87
	v_mul_f32_e32 v64, v64, v88
	s_waitcnt lgkmcnt(2)
	v_pk_add_f32 v[4:5], v[4:5], v[46:47]
	v_mul_f32_e32 v65, v65, v89
	s_waitcnt lgkmcnt(0)
	v_pk_add_f32 v[6:7], v[6:7], v[32:33]
	ds_bpermute_b32 v33, v31, v5
	ds_bpermute_b32 v32, v31, v4
	ds_bpermute_b32 v47, v31, v7
	ds_bpermute_b32 v46, v31, v6
	v_mul_f32_e32 v66, v66, v90
	v_mul_f32_e32 v67, v67, v91
	s_waitcnt lgkmcnt(2)
	v_pk_add_f32 v[4:5], v[4:5], v[32:33]
	ds_bpermute_b32 v33, v30, v5
	s_waitcnt lgkmcnt(1)
	v_pk_add_f32 v[6:7], v[6:7], v[46:47]
	ds_bpermute_b32 v32, v30, v4
	ds_bpermute_b32 v31, v30, v7
	ds_bpermute_b32 v30, v30, v6
	v_mul_f32_e32 v68, v68, v92
	v_mul_f32_e32 v69, v69, v93
	s_waitcnt lgkmcnt(2)
	v_pk_add_f32 v[4:5], v[4:5], v[32:33]
	v_mul_f32_e32 v70, v70, v94
	s_waitcnt lgkmcnt(0)
	v_pk_add_f32 v[6:7], v[6:7], v[30:31]
	v_pk_fma_f32 v[4:5], v[4:5], s[14:15], v[10:11] op_sel_hi:[1,0,0]
	v_pk_fma_f32 v[6:7], v[6:7], s[14:15], v[10:11] op_sel_hi:[1,0,0]
	v_mul_f32_e32 v30, 0x4b800000, v5
	v_cmp_gt_f32_e64 s[6:7], s35, v5
	v_mul_f32_e32 v31, 0x4b800000, v4
	v_cmp_gt_f32_e32 vcc, s35, v4
	v_mul_f32_e32 v32, 0x4b800000, v7
	v_mul_f32_e32 v33, 0x4b800000, v6
	v_cmp_gt_f32_e64 s[0:1], s35, v6
	v_cmp_gt_f32_e64 s[4:5], s35, v7
	v_cndmask_b32_e64 v5, v5, v30, s[6:7]
	v_cndmask_b32_e32 v4, v4, v31, vcc
	v_cndmask_b32_e64 v7, v7, v32, s[4:5]
	v_cndmask_b32_e64 v6, v6, v33, s[0:1]
	v_rsq_f32_e32 v5, v5
	v_rsq_f32_e32 v4, v4
	v_rsq_f32_e32 v7, v7
	v_rsq_f32_e32 v6, v6
	v_mul_f32_e32 v30, 0x45800000, v5
	v_mul_f32_e32 v31, 0x45800000, v4
	v_mul_f32_e32 v32, 0x45800000, v7
	v_mul_f32_e32 v33, 0x45800000, v6
	v_cndmask_b32_e64 v5, v5, v30, s[6:7]
	v_cndmask_b32_e32 v4, v4, v31, vcc
	v_cndmask_b32_e64 v7, v7, v32, s[4:5]
	v_cndmask_b32_e64 v6, v6, v33, s[0:1]
	v_mul_f32_e32 v30, v42, v5
	v_mul_f32_e32 v31, v43, v4
	v_mul_f32_e32 v32, v44, v7
	v_mul_f32_e32 v33, v45, v6
	v_mul_f32_e32 v38, v38, v5
	v_mul_f32_e32 v39, v39, v4
	v_mul_f32_e32 v40, v40, v7
	v_mul_f32_e32 v41, v41, v6
	v_mul_f32_e32 v34, v34, v5
	v_mul_f32_e32 v35, v35, v4
	v_mul_f32_e32 v36, v36, v7
	v_mul_f32_e32 v37, v37, v6
	v_mul_f32_e32 v0, v0, v5
	v_mul_f32_e32 v1, v1, v4
	v_mul_f32_e32 v2, v2, v7
	v_mul_f32_e32 v3, v3, v6
	v_mul_f32_e32 v4, v29, v30
	v_mul_f32_e32 v71, v71, v96
	v_mul_f32_e32 v72, v72, v95
	v_mul_f32_e32 v73, v73, v97
	v_mul_f32_e32 v5, v29, v31
	v_mul_f32_e32 v6, v29, v32
	v_mul_f32_e32 v7, v29, v33
	v_mul_f32_e32 v29, v28, v38
	v_mul_f32_e32 v30, v28, v39
	v_mul_f32_e32 v31, v28, v40
	v_mul_f32_e32 v28, v28, v41
	v_mul_f32_e32 v32, v27, v34
	v_mul_f32_e32 v33, v27, v35
	v_mul_f32_e32 v34, v27, v36
	v_mul_f32_e32 v27, v27, v37
	v_mul_f32_e32 v0, v26, v0
	v_mul_f32_e32 v1, v26, v1
	v_mul_f32_e32 v2, v26, v2
	v_mul_f32_e32 v3, v26, v3
	v_mul_f32_e32 v4, v8, v4
	v_mul_f32_e32 v5, v61, v5
	v_mul_f32_e32 v6, v63, v6
	v_mul_f32_e32 v7, v64, v7
	v_mul_f32_e32 v8, v62, v29
	v_mul_f32_e32 v26, v65, v30
	v_mul_f32_e32 v29, v66, v31
	v_mul_f32_e32 v28, v67, v28
	v_mul_f32_e32 v30, v74, v32
	v_mul_f32_e32 v31, v68, v33
	v_mul_f32_e32 v32, v69, v34
	v_mul_f32_e32 v27, v70, v27
	v_mul_f32_e32 v0, v60, v0
	v_mul_f32_e32 v1, v71, v1
	v_mul_f32_e32 v2, v72, v2
	v_mul_f32_e32 v3, v73, v3
	v_cndmask_b32_e64 v40, v5, v4, s[72:73]
	v_cndmask_b32_e64 v48, v4, v5, s[72:73]
	v_cndmask_b32_e64 v41, v7, v6, s[72:73]
	v_cndmask_b32_e64 v49, v6, v7, s[72:73]
	v_cndmask_b32_e64 v42, v26, v8, s[72:73]
	v_cndmask_b32_e64 v50, v8, v26, s[72:73]
	v_cndmask_b32_e64 v43, v28, v29, s[72:73]
	v_cndmask_b32_e64 v51, v29, v28, s[72:73]
	v_cndmask_b32_e64 v44, v31, v30, s[72:73]
	v_cndmask_b32_e64 v52, v30, v31, s[72:73]
	v_cndmask_b32_e64 v45, v27, v32, s[72:73]
	v_cndmask_b32_e64 v53, v32, v27, s[72:73]
	v_cndmask_b32_e64 v46, v1, v0, s[72:73]
	v_cndmask_b32_e64 v54, v0, v1, s[72:73]
	v_cndmask_b32_e64 v47, v3, v2, s[72:73]
	v_cndmask_b32_e64 v55, v2, v3, s[72:73]
	v_mov_b32_dpp v56, v48 quad_perm:[1,0,3,2] row_mask:0xf bank_mask:0xf
	v_mov_b32_dpp v57, v49 quad_perm:[1,0,3,2] row_mask:0xf bank_mask:0xf
	v_mov_b32_dpp v58, v50 quad_perm:[1,0,3,2] row_mask:0xf bank_mask:0xf
	v_mov_b32_dpp v59, v51 quad_perm:[1,0,3,2] row_mask:0xf bank_mask:0xf
	v_mov_b32_dpp v60, v52 quad_perm:[1,0,3,2] row_mask:0xf bank_mask:0xf
	v_mov_b32_dpp v61, v53 quad_perm:[1,0,3,2] row_mask:0xf bank_mask:0xf
	v_mov_b32_dpp v62, v54 quad_perm:[1,0,3,2] row_mask:0xf bank_mask:0xf
	v_mov_b32_dpp v63, v55 quad_perm:[1,0,3,2] row_mask:0xf bank_mask:0xf
	v_cndmask_b32_e64 v48, v56, v40, s[72:73]
	v_cndmask_b32_e64 v56, v40, v56, s[72:73]
	v_cndmask_b32_e64 v49, v57, v41, s[72:73]
	v_cndmask_b32_e64 v57, v41, v57, s[72:73]
	v_cndmask_b32_e64 v50, v58, v42, s[72:73]
	v_cndmask_b32_e64 v58, v42, v58, s[72:73]
	v_cndmask_b32_e64 v51, v59, v43, s[72:73]
	v_cndmask_b32_e64 v59, v43, v59, s[72:73]
	v_cndmask_b32_e64 v52, v60, v44, s[72:73]
	v_cndmask_b32_e64 v60, v44, v60, s[72:73]
	v_cndmask_b32_e64 v53, v61, v45, s[72:73]
	v_cndmask_b32_e64 v61, v45, v61, s[72:73]
	v_cndmask_b32_e64 v54, v62, v46, s[72:73]
	v_cndmask_b32_e64 v62, v46, v62, s[72:73]
	v_cndmask_b32_e64 v55, v63, v47, s[72:73]
	v_cndmask_b32_e64 v63, v47, v63, s[72:73]
	v_cvt_pk_bf16_f32 v40, v48, v56
	v_cvt_pk_bf16_f32 v41, v49, v57
	v_cvt_pk_bf16_f32 v42, v50, v58
	v_cvt_pk_bf16_f32 v43, v51, v59
	v_cvt_pk_bf16_f32 v44, v52, v60
	v_cvt_pk_bf16_f32 v45, v53, v61
	v_cvt_pk_bf16_f32 v46, v54, v62
	v_cvt_pk_bf16_f32 v47, v55, v63
	global_store_dword v12, v40, s[20:21]
	global_store_dword v16, v41, s[20:21]
	global_store_dword v13, v42, s[20:21]
	global_store_dword v17, v43, s[20:21]
	global_store_dword v12, v44, s[100:101]
	global_store_dword v16, v45, s[100:101]
	global_store_dword v13, v46, s[100:101]
	global_store_dword v17, v47, s[100:101]
	s_cbranch_scc1 .LBB0_1031
